# P0 adaLN GEMV inner loop: 16 weight-row loads in flight per wave instead of one (same accumulation order), on top of v23
# speedup vs baseline: 1.0158x; 1.0065x over previous
.LBB0_91:
	s_add_i32 s2, s16, s17
	s_add_i32 s3, s2, 0x11000
	v_mov_b32_e32 v25, s3
	s_add_i32 s17, s17, 64
	v_add_co_u32_e32 v26, vcc, 0xfffb8000, v4
	s_nop 1
	v_addc_co_u32_e32 v27, vcc, -1, v5, vcc
	global_load_dwordx4 v[32:35], v[26:27], off
	v_add_co_u32_e32 v28, vcc, 0xfffc1000, v4
	s_nop 1
	v_addc_co_u32_e32 v29, vcc, -1, v5, vcc
	global_load_dwordx4 v[36:39], v[28:29], off
	v_add_co_u32_e32 v26, vcc, 0xfffca000, v4
	s_nop 1
	v_addc_co_u32_e32 v27, vcc, -1, v5, vcc
	global_load_dwordx4 v[40:43], v[26:27], off
	v_add_co_u32_e32 v28, vcc, 0xfffd3000, v4
	s_nop 1
	v_addc_co_u32_e32 v29, vcc, -1, v5, vcc
	global_load_dwordx4 v[44:47], v[28:29], off
	v_add_co_u32_e32 v26, vcc, 0xfffdc000, v4
	s_nop 1
	v_addc_co_u32_e32 v27, vcc, -1, v5, vcc
	global_load_dwordx4 v[48:51], v[26:27], off
	v_add_co_u32_e32 v28, vcc, 0xfffe5000, v4
	s_nop 1
	v_addc_co_u32_e32 v29, vcc, -1, v5, vcc
	global_load_dwordx4 v[52:55], v[28:29], off
	v_add_co_u32_e32 v26, vcc, 0xfffee000, v4
	s_nop 1
	v_addc_co_u32_e32 v27, vcc, -1, v5, vcc
	global_load_dwordx4 v[56:59], v[26:27], off
	v_add_co_u32_e32 v28, vcc, 0xffff7000, v4
	s_nop 1
	v_addc_co_u32_e32 v29, vcc, -1, v5, vcc
	global_load_dwordx4 v[60:63], v[28:29], off
	global_load_dwordx4 v[64:67], v[4:5], off
	v_add_co_u32_e32 v28, vcc, 0x9000, v4
	s_nop 1
	v_addc_co_u32_e32 v29, vcc, 0, v5, vcc
	global_load_dwordx4 v[68:71], v[28:29], off
	v_add_co_u32_e32 v26, vcc, 0x12000, v4
	s_nop 1
	v_addc_co_u32_e32 v27, vcc, 0, v5, vcc
	global_load_dwordx4 v[72:75], v[26:27], off
	v_add_co_u32_e32 v28, vcc, 0x1b000, v4
	s_nop 1
	v_addc_co_u32_e32 v29, vcc, 0, v5, vcc
	global_load_dwordx4 v[76:79], v[28:29], off
	v_add_co_u32_e32 v26, vcc, 0x24000, v4
	s_nop 1
	v_addc_co_u32_e32 v27, vcc, 0, v5, vcc
	global_load_dwordx4 v[80:83], v[26:27], off
	v_add_co_u32_e32 v28, vcc, 0x2d000, v4
	s_nop 1
	v_addc_co_u32_e32 v29, vcc, 0, v5, vcc
	global_load_dwordx4 v[84:87], v[28:29], off
	v_add_co_u32_e32 v26, vcc, 0x36000, v4
	s_nop 1
	v_addc_co_u32_e32 v27, vcc, 0, v5, vcc
	global_load_dwordx4 v[88:91], v[26:27], off
	v_add_co_u32_e32 v28, vcc, 0x3f000, v4
	s_nop 1
	v_addc_co_u32_e32 v29, vcc, 0, v5, vcc
	global_load_dwordx4 v[92:95], v[28:29], off
	ds_read_b128 v[136:139], v25
	ds_read_b128 v[152:155], v25 offset:4096
	ds_read_b128 v[168:171], v25 offset:8192
	ds_read_b128 v[140:143], v25 offset:16
	ds_read_b128 v[156:159], v25 offset:4112
	ds_read_b128 v[172:175], v25 offset:8208
	ds_read_b128 v[144:147], v25 offset:32
	ds_read_b128 v[160:163], v25 offset:4128
	ds_read_b128 v[176:179], v25 offset:8224
	ds_read_b128 v[148:151], v25 offset:48
	ds_read_b128 v[164:167], v25 offset:4144
	ds_read_b128 v[180:183], v25 offset:8240
	s_mov_b64 s[2:3], 0x90000
	s_waitcnt lgkmcnt(0)
	s_waitcnt vmcnt(15)
	v_pk_fma_f32 v[8:9], v[32:33], v[136:137], v[8:9] op_sel_hi:[1,0,1]
	v_pk_fma_f32 v[6:7], v[34:35], v[136:137], v[6:7] op_sel_hi:[1,0,1]
	v_pk_fma_f32 v[14:15], v[32:33], v[152:153], v[14:15] op_sel_hi:[1,0,1]
	v_pk_fma_f32 v[10:11], v[34:35], v[152:153], v[10:11] op_sel_hi:[1,0,1]
	v_pk_fma_f32 v[16:17], v[32:33], v[168:169], v[16:17] op_sel_hi:[1,0,1]
	v_pk_fma_f32 v[12:13], v[34:35], v[168:169], v[12:13] op_sel_hi:[1,0,1]
	s_waitcnt vmcnt(14)
	v_pk_fma_f32 v[8:9], v[36:37], v[136:137], v[8:9] op_sel:[0,1,0]
	v_pk_fma_f32 v[6:7], v[38:39], v[136:137], v[6:7] op_sel:[0,1,0]
	v_pk_fma_f32 v[14:15], v[36:37], v[152:153], v[14:15] op_sel:[0,1,0]
	v_pk_fma_f32 v[10:11], v[38:39], v[152:153], v[10:11] op_sel:[0,1,0]
	v_pk_fma_f32 v[16:17], v[36:37], v[168:169], v[16:17] op_sel:[0,1,0]
	v_pk_fma_f32 v[12:13], v[38:39], v[168:169], v[12:13] op_sel:[0,1,0]
	s_waitcnt vmcnt(13)
	v_pk_fma_f32 v[8:9], v[40:41], v[138:139], v[8:9] op_sel_hi:[1,0,1]
	v_pk_fma_f32 v[6:7], v[42:43], v[138:139], v[6:7] op_sel_hi:[1,0,1]
	v_pk_fma_f32 v[14:15], v[40:41], v[154:155], v[14:15] op_sel_hi:[1,0,1]
	v_pk_fma_f32 v[10:11], v[42:43], v[154:155], v[10:11] op_sel_hi:[1,0,1]
	v_pk_fma_f32 v[16:17], v[40:41], v[170:171], v[16:17] op_sel_hi:[1,0,1]
	v_pk_fma_f32 v[12:13], v[42:43], v[170:171], v[12:13] op_sel_hi:[1,0,1]
	s_waitcnt vmcnt(12)
	v_pk_fma_f32 v[8:9], v[44:45], v[138:139], v[8:9] op_sel:[0,1,0]
	v_pk_fma_f32 v[6:7], v[46:47], v[138:139], v[6:7] op_sel:[0,1,0]
	v_pk_fma_f32 v[14:15], v[44:45], v[154:155], v[14:15] op_sel:[0,1,0]
	v_pk_fma_f32 v[10:11], v[46:47], v[154:155], v[10:11] op_sel:[0,1,0]
	v_pk_fma_f32 v[16:17], v[44:45], v[170:171], v[16:17] op_sel:[0,1,0]
	v_pk_fma_f32 v[12:13], v[46:47], v[170:171], v[12:13] op_sel:[0,1,0]
	s_waitcnt vmcnt(11)
	v_pk_fma_f32 v[8:9], v[48:49], v[140:141], v[8:9] op_sel_hi:[1,0,1]
	v_pk_fma_f32 v[6:7], v[50:51], v[140:141], v[6:7] op_sel_hi:[1,0,1]
	v_pk_fma_f32 v[14:15], v[48:49], v[156:157], v[14:15] op_sel_hi:[1,0,1]
	v_pk_fma_f32 v[10:11], v[50:51], v[156:157], v[10:11] op_sel_hi:[1,0,1]
	v_pk_fma_f32 v[16:17], v[48:49], v[172:173], v[16:17] op_sel_hi:[1,0,1]
	v_pk_fma_f32 v[12:13], v[50:51], v[172:173], v[12:13] op_sel_hi:[1,0,1]
	s_waitcnt vmcnt(10)
	v_pk_fma_f32 v[8:9], v[52:53], v[140:141], v[8:9] op_sel:[0,1,0]
	v_pk_fma_f32 v[6:7], v[54:55], v[140:141], v[6:7] op_sel:[0,1,0]
	v_pk_fma_f32 v[14:15], v[52:53], v[156:157], v[14:15] op_sel:[0,1,0]
	v_pk_fma_f32 v[10:11], v[54:55], v[156:157], v[10:11] op_sel:[0,1,0]
	v_pk_fma_f32 v[16:17], v[52:53], v[172:173], v[16:17] op_sel:[0,1,0]
	v_pk_fma_f32 v[12:13], v[54:55], v[172:173], v[12:13] op_sel:[0,1,0]
	s_waitcnt vmcnt(9)
	v_pk_fma_f32 v[8:9], v[56:57], v[142:143], v[8:9] op_sel_hi:[1,0,1]
	v_pk_fma_f32 v[6:7], v[58:59], v[142:143], v[6:7] op_sel_hi:[1,0,1]
	v_pk_fma_f32 v[14:15], v[56:57], v[158:159], v[14:15] op_sel_hi:[1,0,1]
	v_pk_fma_f32 v[10:11], v[58:59], v[158:159], v[10:11] op_sel_hi:[1,0,1]
	v_pk_fma_f32 v[16:17], v[56:57], v[174:175], v[16:17] op_sel_hi:[1,0,1]
	v_pk_fma_f32 v[12:13], v[58:59], v[174:175], v[12:13] op_sel_hi:[1,0,1]
	s_waitcnt vmcnt(8)
	v_pk_fma_f32 v[8:9], v[60:61], v[142:143], v[8:9] op_sel:[0,1,0]
	v_pk_fma_f32 v[6:7], v[62:63], v[142:143], v[6:7] op_sel:[0,1,0]
	v_pk_fma_f32 v[14:15], v[60:61], v[158:159], v[14:15] op_sel:[0,1,0]
	v_pk_fma_f32 v[10:11], v[62:63], v[158:159], v[10:11] op_sel:[0,1,0]
	v_pk_fma_f32 v[16:17], v[60:61], v[174:175], v[16:17] op_sel:[0,1,0]
	v_pk_fma_f32 v[12:13], v[62:63], v[174:175], v[12:13] op_sel:[0,1,0]
	s_waitcnt vmcnt(7)
	v_pk_fma_f32 v[8:9], v[64:65], v[144:145], v[8:9] op_sel_hi:[1,0,1]
	v_pk_fma_f32 v[6:7], v[66:67], v[144:145], v[6:7] op_sel_hi:[1,0,1]
	v_pk_fma_f32 v[14:15], v[64:65], v[160:161], v[14:15] op_sel_hi:[1,0,1]
	v_pk_fma_f32 v[10:11], v[66:67], v[160:161], v[10:11] op_sel_hi:[1,0,1]
	v_pk_fma_f32 v[16:17], v[64:65], v[176:177], v[16:17] op_sel_hi:[1,0,1]
	v_pk_fma_f32 v[12:13], v[66:67], v[176:177], v[12:13] op_sel_hi:[1,0,1]
	s_waitcnt vmcnt(6)
	v_pk_fma_f32 v[8:9], v[68:69], v[144:145], v[8:9] op_sel:[0,1,0]
	v_pk_fma_f32 v[6:7], v[70:71], v[144:145], v[6:7] op_sel:[0,1,0]
	v_pk_fma_f32 v[14:15], v[68:69], v[160:161], v[14:15] op_sel:[0,1,0]
	v_pk_fma_f32 v[10:11], v[70:71], v[160:161], v[10:11] op_sel:[0,1,0]
	v_pk_fma_f32 v[16:17], v[68:69], v[176:177], v[16:17] op_sel:[0,1,0]
	v_pk_fma_f32 v[12:13], v[70:71], v[176:177], v[12:13] op_sel:[0,1,0]
	s_waitcnt vmcnt(5)
	v_pk_fma_f32 v[8:9], v[72:73], v[146:147], v[8:9] op_sel_hi:[1,0,1]
	v_pk_fma_f32 v[6:7], v[74:75], v[146:147], v[6:7] op_sel_hi:[1,0,1]
	v_pk_fma_f32 v[14:15], v[72:73], v[162:163], v[14:15] op_sel_hi:[1,0,1]
	v_pk_fma_f32 v[10:11], v[74:75], v[162:163], v[10:11] op_sel_hi:[1,0,1]
	v_pk_fma_f32 v[16:17], v[72:73], v[178:179], v[16:17] op_sel_hi:[1,0,1]
	v_pk_fma_f32 v[12:13], v[74:75], v[178:179], v[12:13] op_sel_hi:[1,0,1]
	s_waitcnt vmcnt(4)
	v_pk_fma_f32 v[8:9], v[76:77], v[146:147], v[8:9] op_sel:[0,1,0]
	v_pk_fma_f32 v[6:7], v[78:79], v[146:147], v[6:7] op_sel:[0,1,0]
	v_pk_fma_f32 v[14:15], v[76:77], v[162:163], v[14:15] op_sel:[0,1,0]
	v_pk_fma_f32 v[10:11], v[78:79], v[162:163], v[10:11] op_sel:[0,1,0]
	v_pk_fma_f32 v[16:17], v[76:77], v[178:179], v[16:17] op_sel:[0,1,0]
	v_pk_fma_f32 v[12:13], v[78:79], v[178:179], v[12:13] op_sel:[0,1,0]
	s_waitcnt vmcnt(3)
	v_pk_fma_f32 v[8:9], v[80:81], v[148:149], v[8:9] op_sel_hi:[1,0,1]
	v_pk_fma_f32 v[6:7], v[82:83], v[148:149], v[6:7] op_sel_hi:[1,0,1]
	v_pk_fma_f32 v[14:15], v[80:81], v[164:165], v[14:15] op_sel_hi:[1,0,1]
	v_pk_fma_f32 v[10:11], v[82:83], v[164:165], v[10:11] op_sel_hi:[1,0,1]
	v_pk_fma_f32 v[16:17], v[80:81], v[180:181], v[16:17] op_sel_hi:[1,0,1]
	v_pk_fma_f32 v[12:13], v[82:83], v[180:181], v[12:13] op_sel_hi:[1,0,1]
	s_waitcnt vmcnt(2)
	v_pk_fma_f32 v[8:9], v[84:85], v[148:149], v[8:9] op_sel:[0,1,0]
	v_pk_fma_f32 v[6:7], v[86:87], v[148:149], v[6:7] op_sel:[0,1,0]
	v_pk_fma_f32 v[14:15], v[84:85], v[164:165], v[14:15] op_sel:[0,1,0]
	v_pk_fma_f32 v[10:11], v[86:87], v[164:165], v[10:11] op_sel:[0,1,0]
	v_pk_fma_f32 v[16:17], v[84:85], v[180:181], v[16:17] op_sel:[0,1,0]
	v_pk_fma_f32 v[12:13], v[86:87], v[180:181], v[12:13] op_sel:[0,1,0]
	s_waitcnt vmcnt(1)
	v_pk_fma_f32 v[8:9], v[88:89], v[150:151], v[8:9] op_sel_hi:[1,0,1]
	v_pk_fma_f32 v[6:7], v[90:91], v[150:151], v[6:7] op_sel_hi:[1,0,1]
	v_pk_fma_f32 v[14:15], v[88:89], v[166:167], v[14:15] op_sel_hi:[1,0,1]
	v_pk_fma_f32 v[10:11], v[90:91], v[166:167], v[10:11] op_sel_hi:[1,0,1]
	v_pk_fma_f32 v[16:17], v[88:89], v[182:183], v[16:17] op_sel_hi:[1,0,1]
	v_pk_fma_f32 v[12:13], v[90:91], v[182:183], v[12:13] op_sel_hi:[1,0,1]
	s_waitcnt vmcnt(0)
	v_pk_fma_f32 v[8:9], v[92:93], v[150:151], v[8:9] op_sel:[0,1,0]
	v_pk_fma_f32 v[6:7], v[94:95], v[150:151], v[6:7] op_sel:[0,1,0]
	v_pk_fma_f32 v[14:15], v[92:93], v[166:167], v[14:15] op_sel:[0,1,0]
	v_pk_fma_f32 v[10:11], v[94:95], v[166:167], v[10:11] op_sel:[0,1,0]
	v_pk_fma_f32 v[16:17], v[92:93], v[182:183], v[16:17] op_sel:[0,1,0]
	v_pk_fma_f32 v[12:13], v[94:95], v[182:183], v[12:13] op_sel:[0,1,0]
	v_lshl_add_u64 v[4:5], v[4:5], 0, s[2:3]
	s_cmpk_eq_i32 s17, 0x100
	s_cbranch_scc0 .LBB0_91
	s_and_b32 s2, s14, 15
	s_cmp_eq_u32 s2, 0
	s_cbranch_scc0 .LBB0_89
	v_readlane_b32 s68, v249, 2
	v_readlane_b32 s78, v249, 12
	v_readlane_b32 s79, v249, 13
	s_mul_i32 s2, s15, 0x9000
	s_mov_b64 s[18:19], s[78:79]
	s_mul_hi_i32 s3, s15, 0x9000
	s_add_u32 s2, s18, s2
	s_addc_u32 s3, s19, s3
	v_lshl_add_u64 v[4:5], v[2:3], 2, s[2:3]
	global_load_dwordx4 v[26:29], v[4:5], off
	v_readlane_b32 s69, v249, 3
	v_readlane_b32 s70, v249, 4
	v_readlane_b32 s71, v249, 5
	v_readlane_b32 s72, v249, 6
	v_readlane_b32 s73, v249, 7
	v_readlane_b32 s74, v249, 8
	v_readlane_b32 s75, v249, 9
	v_readlane_b32 s76, v249, 10
	v_readlane_b32 s77, v249, 11
	v_readlane_b32 s80, v249, 14
	v_readlane_b32 s81, v249, 15
	v_readlane_b32 s82, v249, 16
	v_readlane_b32 s83, v249, 17
	s_waitcnt vmcnt(0)
	v_pk_add_f32 v[6:7], v[6:7], v[28:29]
	v_pk_add_f32 v[8:9], v[8:9], v[26:27]
	v_pk_add_f32 v[10:11], v[10:11], v[28:29]
	v_pk_add_f32 v[14:15], v[14:15], v[26:27]
	v_pk_add_f32 v[12:13], v[12:13], v[28:29]
	v_pk_add_f32 v[16:17], v[16:17], v[26:27]
	s_branch .LBB0_89
